# v23 + GEMM tile prologues: accumulators v18..v129 cleared by seven 0*0+0 32x32x16 MFMAs (idle matrix pipe) instead of 112 v_mov; v3..v17 by v_mov interleaved
# speedup vs baseline: 1.0052x; 1.0045x over previous
; template <class Epi>
; __device__ __forceinline__ void gemm_phase(LAS unsigned char* lds, int wave_s, const Gemm g, const StaticOrder S, const Epi E) {
;     ...
;         const bool has_next = S.next(ui + 1, nxt);
;         const char* nA = has_next ? (const char*)g.A + (size_t)nxt.pm * tstepA : cA; const char* nB = has_next ? (const char*)g.Bt + (size_t)nxt.pn * tstepB : cB;
;     ...
; #pragma unroll
;         for (int a = 0; a < 2; ++a)
; #pragma unroll
;             for (int b = 0; b < 2; ++b)
; #pragma unroll
;                 for (int m = 0; m < 4; ++m)
; #pragma unroll
;                     for (int n = 0; n < 2; ++n) acc[a][b][m][n] = (f32x4){0.f, 0.f, 0.f, 0.f};
.LBB0_164:
	s_ashr_i32 s19, s18, 31
	s_lshl_b64 s[6:7], s[18:19], 19
	s_add_u32 s20, s38, s6
	s_addc_u32 s21, s39, s7
	s_and_b64 s[6:7], s[0:1], exec
	s_cselect_b32 s19, s21, s25
	s_cselect_b32 s45, s20, s24
	s_ashr_i32 s17, s16, 31
	s_lshl_b64 s[6:7], s[16:17], 19
	v_readlane_b32 s10, v252, 43
	v_readlane_b32 s11, v252, 44
	s_add_u32 s22, s10, s6
	s_addc_u32 s23, s11, s7
	s_and_b64 s[6:7], s[0:1], exec
	s_cselect_b32 s10, s23, s27
	s_cselect_b32 s11, s22, s26
	s_add_u32 s24, s24, 0x40080
	s_addc_u32 s25, s25, 0
	s_add_u32 s17, s26, 0x100
	v_mov_b32_e32 v2, 0
	s_addc_u32 s46, s27, 0
	s_mov_b32 s47, -2
	v_mov_b32_e32 v246, v2
	v_mov_b32_e32 v247, v2
	v_mov_b32_e32 v248, v2
	v_mov_b32_e32 v249, v2
	v_mov_b32_e32 v3, v2
	v_mov_b32_e32 v4, v2
	v_mfma_f32_32x32x16_bf16 v[18:33], v[246:249], v[246:249], 0
	v_mov_b32_e32 v5, v2
	v_mov_b32_e32 v6, v2
	v_mfma_f32_32x32x16_bf16 v[34:49], v[246:249], v[246:249], 0
	v_mov_b32_e32 v7, v2
	v_mov_b32_e32 v8, v2
	v_mfma_f32_32x32x16_bf16 v[50:65], v[246:249], v[246:249], 0
	v_mov_b32_e32 v9, v2
	v_mov_b32_e32 v10, v2
	v_mfma_f32_32x32x16_bf16 v[66:81], v[246:249], v[246:249], 0
	v_mov_b32_e32 v11, v2
	v_mov_b32_e32 v12, v2
	v_mfma_f32_32x32x16_bf16 v[82:97], v[246:249], v[246:249], 0
	v_mov_b32_e32 v13, v2
	v_mov_b32_e32 v14, v2
	v_mfma_f32_32x32x16_bf16 v[98:113], v[246:249], v[246:249], 0
	v_mov_b32_e32 v15, v2
	v_mov_b32_e32 v16, v2
	v_mfma_f32_32x32x16_bf16 v[114:129], v[246:249], v[246:249], 0
	v_mov_b32_e32 v17, v2

; template <class Epi>
; __device__ __forceinline__ void gemm_phase(LAS unsigned char* lds, int wave_s, const Gemm g, const StaticOrder S, const Epi E) {
;     ...
; #pragma unroll
;         for (int a = 0; a < 2; ++a)
; #pragma unroll
;             for (int b = 0; b < 2; ++b)
; #pragma unroll
;                 for (int m = 0; m < 4; ++m)
; #pragma unroll
;                     for (int n = 0; n < 2; ++n) acc[a][b][m][n] = (f32x4){0.f, 0.f, 0.f, 0.f};
.LBB0_240:
	s_add_u32 s10, s14, 0x100
	v_mov_b32_e32 v2, 0
	s_addc_u32 s11, s15, 0
	s_mov_b32 s34, -2
	v_mov_b32_e32 v246, v2
	v_mov_b32_e32 v247, v2
	v_mov_b32_e32 v248, v2
	v_mov_b32_e32 v249, v2
	v_mov_b32_e32 v3, v2
	v_mov_b32_e32 v4, v2
	v_mfma_f32_32x32x16_bf16 v[18:33], v[246:249], v[246:249], 0
	v_mov_b32_e32 v5, v2
	v_mov_b32_e32 v6, v2
	v_mfma_f32_32x32x16_bf16 v[34:49], v[246:249], v[246:249], 0
	v_mov_b32_e32 v7, v2
	v_mov_b32_e32 v8, v2
	v_mfma_f32_32x32x16_bf16 v[50:65], v[246:249], v[246:249], 0
	v_mov_b32_e32 v9, v2
	v_mov_b32_e32 v10, v2
	v_mfma_f32_32x32x16_bf16 v[66:81], v[246:249], v[246:249], 0
	v_mov_b32_e32 v11, v2
	v_mov_b32_e32 v12, v2
	v_mfma_f32_32x32x16_bf16 v[82:97], v[246:249], v[246:249], 0
	v_mov_b32_e32 v13, v2
	v_mov_b32_e32 v14, v2
	v_mfma_f32_32x32x16_bf16 v[98:113], v[246:249], v[246:249], 0
	v_mov_b32_e32 v15, v2
	v_mov_b32_e32 v16, v2
	v_mfma_f32_32x32x16_bf16 v[114:129], v[246:249], v[246:249], 0
	v_mov_b32_e32 v17, v2

; template <class Epi>
; __device__ __forceinline__ void gemm_phase(LAS unsigned char* lds, int wave_s, const Gemm g, const StaticOrder S, const Epi E) {
;     ...
;         const bool has_next = S.next(ui + 1, nxt);
;         const char* nA = has_next ? (const char*)g.A + (size_t)nxt.pm * tstepA : cA; const char* nB = has_next ? (const char*)g.Bt + (size_t)nxt.pn * tstepB : cB;
;     ...
; #pragma unroll
;         for (int a = 0; a < 2; ++a)
; #pragma unroll
;             for (int b = 0; b < 2; ++b)
; #pragma unroll
;                 for (int m = 0; m < 4; ++m)
; #pragma unroll
;                     for (int n = 0; n < 2; ++n) acc[a][b][m][n] = (f32x4){0.f, 0.f, 0.f, 0.f};
.LBB0_327:
	s_ashr_i32 s23, s22, 31
	s_lshl_b64 s[6:7], s[22:23], 19
	s_add_u32 s24, s50, s6
	s_addc_u32 s25, s51, s7
	s_and_b64 s[6:7], s[48:49], exec
	s_cselect_b32 s23, s25, s1
	s_cselect_b32 s34, s24, s0
	s_ashr_i32 s21, s20, 31
	s_lshl_b64 s[6:7], s[20:21], 19
	v_readlane_b32 s10, v250, 33
	v_readlane_b32 s11, v250, 34
	s_add_u32 s26, s10, s6
	s_addc_u32 s27, s11, s7
	s_and_b64 s[6:7], s[48:49], exec
	s_cselect_b32 s10, s27, s29
	s_cselect_b32 s11, s26, s28
	s_add_u32 s0, s0, 0x40080
	s_addc_u32 s1, s1, 0
	s_add_u32 s21, s28, 0x100
	v_mov_b32_e32 v2, 0
	s_addc_u32 s35, s29, 0
	s_mov_b32 s50, -2
	v_mov_b32_e32 v3, v2
	v_mov_b32_e32 v4, v2
	v_mov_b32_e32 v5, v2
	v_mov_b32_e32 v6, v2
	v_mov_b32_e32 v7, v2
	v_mov_b32_e32 v8, v2
	v_mov_b32_e32 v9, v2
	v_mov_b32_e32 v10, v2
	s_waitcnt lgkmcnt(0)
	v_mov_b32_e32 v246, v2
	v_mov_b32_e32 v247, v2
	v_mov_b32_e32 v248, v2
	v_mov_b32_e32 v249, v2
	v_mov_b32_e32 v11, v2
	v_mov_b32_e32 v12, v2
	v_mfma_f32_32x32x16_bf16 v[18:33], v[246:249], v[246:249], 0
	v_mov_b32_e32 v13, v2
	v_mov_b32_e32 v14, v2
	v_mfma_f32_32x32x16_bf16 v[34:49], v[246:249], v[246:249], 0
	v_mov_b32_e32 v15, v2
	v_mov_b32_e32 v16, v2
	v_mfma_f32_32x32x16_bf16 v[50:65], v[246:249], v[246:249], 0
	v_mov_b32_e32 v17, v2
	v_mfma_f32_32x32x16_bf16 v[66:81], v[246:249], v[246:249], 0
	v_mfma_f32_32x32x16_bf16 v[82:97], v[246:249], v[246:249], 0
	v_mfma_f32_32x32x16_bf16 v[98:113], v[246:249], v[246:249], 0
	v_mfma_f32_32x32x16_bf16 v[114:129], v[246:249], v[246:249], 0

; template <class Epi>
; __device__ __forceinline__ void gemm_phase(LAS unsigned char* lds, int wave_s, const Gemm g, const StaticOrder S, const Epi E) {
;     ...
; #pragma unroll
;         for (int a = 0; a < 2; ++a)
; #pragma unroll
;             for (int b = 0; b < 2; ++b)
; #pragma unroll
;                 for (int m = 0; m < 4; ++m)
; #pragma unroll
;                     for (int n = 0; n < 2; ++n) acc[a][b][m][n] = (f32x4){0.f, 0.f, 0.f, 0.f};
.LBB0_564:
	s_add_u32 s10, s20, 0x100
	v_mov_b32_e32 v2, 0
	s_addc_u32 s11, s21, 0
	s_mov_b32 s50, -2
	v_mov_b32_e32 v246, v2
	v_mov_b32_e32 v247, v2
	v_mov_b32_e32 v248, v2
	v_mov_b32_e32 v249, v2
	v_mov_b32_e32 v3, v2
	v_mov_b32_e32 v4, v2
	v_mfma_f32_32x32x16_bf16 v[18:33], v[246:249], v[246:249], 0
	v_mov_b32_e32 v5, v2
	v_mov_b32_e32 v6, v2
	v_mfma_f32_32x32x16_bf16 v[34:49], v[246:249], v[246:249], 0
	v_mov_b32_e32 v7, v2
	v_mov_b32_e32 v8, v2
	v_mfma_f32_32x32x16_bf16 v[50:65], v[246:249], v[246:249], 0
	v_mov_b32_e32 v9, v2
	v_mov_b32_e32 v10, v2
	v_mfma_f32_32x32x16_bf16 v[66:81], v[246:249], v[246:249], 0
	v_mov_b32_e32 v11, v2
	v_mov_b32_e32 v12, v2
	v_mfma_f32_32x32x16_bf16 v[82:97], v[246:249], v[246:249], 0
	v_mov_b32_e32 v13, v2
	v_mov_b32_e32 v14, v2
	v_mfma_f32_32x32x16_bf16 v[98:113], v[246:249], v[246:249], 0
	v_mov_b32_e32 v15, v2
	v_mov_b32_e32 v16, v2
	v_mfma_f32_32x32x16_bf16 v[114:129], v[246:249], v[246:249], 0
	v_mov_b32_e32 v17, v2

; template <class Epi>
; __device__ __forceinline__ void gemm_phase(LAS unsigned char* lds, int wave_s, const Gemm g, const StaticOrder S, const Epi E) {
;     ...
;         const bool has_next = S.next(ui + 1, nxt);
;         const char* nA = has_next ? (const char*)g.A + (size_t)nxt.pm * tstepA : cA; const char* nB = has_next ? (const char*)g.Bt + (size_t)nxt.pn * tstepB : cB;
;     ...
; #pragma unroll
;         for (int a = 0; a < 2; ++a)
; #pragma unroll
;             for (int b = 0; b < 2; ++b)
; #pragma unroll
;                 for (int m = 0; m < 4; ++m)
; #pragma unroll
;                     for (int n = 0; n < 2; ++n) acc[a][b][m][n] = (f32x4){0.f, 0.f, 0.f, 0.f};
.LBB0_634:
	s_ashr_i32 s17, s16, 31
	s_lshl_b64 s[6:7], s[16:17], 17
	v_readlane_b32 s10, v255, 55
	v_readlane_b32 s11, v255, 56
	s_add_u32 s20, s10, s6
	s_addc_u32 s21, s11, s7
	s_and_b64 s[0:1], s[0:1], exec
	v_mov_b32_e32 v2, 0
	s_cselect_b32 s17, s21, s23
	s_cselect_b32 s10, s20, s22
	s_mov_b32 s11, 0
	s_mov_b64 s[0:1], -1
	s_mov_b64 s[26:27], 0
	v_mov_b32_e32 v246, v2
	v_mov_b32_e32 v247, v2
	v_mov_b32_e32 v248, v2
	v_mov_b32_e32 v249, v2
	v_mov_b32_e32 v3, v2
	v_mov_b32_e32 v4, v2
	v_mfma_f32_32x32x16_bf16 v[18:33], v[246:249], v[246:249], 0
	v_mov_b32_e32 v5, v2
	v_mov_b32_e32 v6, v2
	v_mfma_f32_32x32x16_bf16 v[34:49], v[246:249], v[246:249], 0
	v_mov_b32_e32 v7, v2
	v_mov_b32_e32 v8, v2
	v_mfma_f32_32x32x16_bf16 v[50:65], v[246:249], v[246:249], 0
	v_mov_b32_e32 v9, v2
	v_mov_b32_e32 v10, v2
	v_mfma_f32_32x32x16_bf16 v[66:81], v[246:249], v[246:249], 0
	v_mov_b32_e32 v11, v2
	v_mov_b32_e32 v12, v2
	v_mfma_f32_32x32x16_bf16 v[82:97], v[246:249], v[246:249], 0
	v_mov_b32_e32 v13, v2
	v_mov_b32_e32 v14, v2
	v_mfma_f32_32x32x16_bf16 v[98:113], v[246:249], v[246:249], 0
	v_mov_b32_e32 v15, v2
	v_mov_b32_e32 v16, v2
	v_mfma_f32_32x32x16_bf16 v[114:129], v[246:249], v[246:249], 0
	v_mov_b32_e32 v17, v2

; template <class Epi>
; __device__ __forceinline__ void gemm_phase(LAS unsigned char* lds, int wave_s, const Gemm g, const StaticOrder S, const Epi E) {
;     ...
;         const bool has_next = S.next(ui + 1, nxt);
;         const char* nA = has_next ? (const char*)g.A + (size_t)nxt.pm * tstepA : cA; const char* nB = has_next ? (const char*)g.Bt + (size_t)nxt.pn * tstepB : cB;
;     ...
; #pragma unroll
;         for (int a = 0; a < 2; ++a)
; #pragma unroll
;             for (int b = 0; b < 2; ++b)
; #pragma unroll
;                 for (int m = 0; m < 4; ++m)
; #pragma unroll
;                     for (int n = 0; n < 2; ++n) acc[a][b][m][n] = (f32x4){0.f, 0.f, 0.f, 0.f};
.LBB0_1067:
	s_ashr_i32 s21, s20, 31
	s_lshl_b64 s[6:7], s[20:21], 19
	v_readlane_b32 s10, v253, 6
	v_readlane_b32 s11, v253, 7
	s_add_u32 s24, s10, s6
	s_addc_u32 s25, s11, s7
	s_and_b64 s[0:1], s[0:1], exec
	s_cselect_b32 s10, s25, s29
	s_cselect_b32 s11, s24, s28
	s_add_u32 s21, s28, 0x100
	v_mov_b32_e32 v2, 0
	s_addc_u32 s52, s29, 0
	s_mov_b32 s53, -2
	v_mov_b32_e32 v246, v2
	v_mov_b32_e32 v247, v2
	v_mov_b32_e32 v248, v2
	v_mov_b32_e32 v249, v2
	v_mov_b32_e32 v3, v2
	v_mov_b32_e32 v4, v2
	v_mfma_f32_32x32x16_bf16 v[18:33], v[246:249], v[246:249], 0
	v_mov_b32_e32 v5, v2
	v_mov_b32_e32 v6, v2
	v_mfma_f32_32x32x16_bf16 v[34:49], v[246:249], v[246:249], 0
	v_mov_b32_e32 v7, v2
	v_mov_b32_e32 v8, v2
	v_mfma_f32_32x32x16_bf16 v[50:65], v[246:249], v[246:249], 0
	v_mov_b32_e32 v9, v2
	v_mov_b32_e32 v10, v2
	v_mfma_f32_32x32x16_bf16 v[66:81], v[246:249], v[246:249], 0
	v_mov_b32_e32 v11, v2
	v_mov_b32_e32 v12, v2
	v_mfma_f32_32x32x16_bf16 v[82:97], v[246:249], v[246:249], 0
	v_mov_b32_e32 v13, v2
	v_mov_b32_e32 v14, v2
	v_mfma_f32_32x32x16_bf16 v[98:113], v[246:249], v[246:249], 0
	v_mov_b32_e32 v15, v2
	v_mov_b32_e32 v16, v2
	v_mfma_f32_32x32x16_bf16 v[114:129], v[246:249], v[246:249], 0
	v_mov_b32_e32 v17, v2

; template <class Epi>
; __device__ __forceinline__ void gemm_phase(LAS unsigned char* lds, int wave_s, const Gemm g, const StaticOrder S, const Epi E) {
;     ...
;         const bool has_next = S.next(ui + 1, nxt);
;         const char* nA = has_next ? (const char*)g.A + (size_t)nxt.pm * tstepA : cA; const char* nB = has_next ? (const char*)g.Bt + (size_t)nxt.pn * tstepB : cB;
;     ...
; #pragma unroll
;         for (int a = 0; a < 2; ++a)
; #pragma unroll
;             for (int b = 0; b < 2; ++b)
; #pragma unroll
;                 for (int m = 0; m < 4; ++m)
; #pragma unroll
;                     for (int n = 0; n < 2; ++n) acc[a][b][m][n] = (f32x4){0.f, 0.f, 0.f, 0.f};
.LBB0_1150:
	s_ashr_i32 s17, s16, 31
	s_lshl_b64 s[6:7], s[16:17], 19
	v_readlane_b32 s10, v253, 35
	v_readlane_b32 s11, v253, 36
	s_add_u32 s18, s10, s6
	s_addc_u32 s19, s11, s7
	s_and_b64 s[6:7], s[42:43], exec
	s_cselect_b32 s17, s19, s23
	s_cselect_b32 s40, s18, s22
	s_ashr_i32 s15, s14, 31
	s_lshl_b64 s[6:7], s[14:15], 19
	v_readlane_b32 s10, v252, 54
	v_readlane_b32 s11, v252, 55
	s_add_u32 s20, s10, s6
	s_addc_u32 s21, s11, s7
	s_and_b64 s[6:7], s[42:43], exec
	s_cselect_b32 s10, s21, s25
	s_cselect_b32 s11, s20, s24
	s_add_u32 s22, s22, 0x40080
	s_addc_u32 s23, s23, 0
	s_add_u32 s15, s24, 0x100
	v_mov_b32_e32 v2, 0
	s_addc_u32 s44, s25, 0
	s_mov_b32 s45, -2
	v_mov_b32_e32 v246, v2
	v_mov_b32_e32 v247, v2
	v_mov_b32_e32 v248, v2
	v_mov_b32_e32 v249, v2
	v_mov_b32_e32 v3, v2
	v_mov_b32_e32 v4, v2
	v_mfma_f32_32x32x16_bf16 v[18:33], v[246:249], v[246:249], 0
	v_mov_b32_e32 v5, v2
	v_mov_b32_e32 v6, v2
	v_mfma_f32_32x32x16_bf16 v[34:49], v[246:249], v[246:249], 0
	v_mov_b32_e32 v7, v2
	v_mov_b32_e32 v8, v2
	v_mfma_f32_32x32x16_bf16 v[50:65], v[246:249], v[246:249], 0
	v_mov_b32_e32 v9, v2
	v_mov_b32_e32 v10, v2
	v_mfma_f32_32x32x16_bf16 v[66:81], v[246:249], v[246:249], 0
	v_mov_b32_e32 v11, v2
	v_mov_b32_e32 v12, v2
	v_mfma_f32_32x32x16_bf16 v[82:97], v[246:249], v[246:249], 0
	v_mov_b32_e32 v13, v2
	v_mov_b32_e32 v14, v2
	v_mfma_f32_32x32x16_bf16 v[98:113], v[246:249], v[246:249], 0
	v_mov_b32_e32 v15, v2
	v_mov_b32_e32 v16, v2
	v_mfma_f32_32x32x16_bf16 v[114:129], v[246:249], v[246:249], 0
	v_mov_b32_e32 v17, v2

; template <class Epi>
; __device__ __forceinline__ void gemm_phase(LAS unsigned char* lds, int wave_s, const Gemm g, const StaticOrder S, const Epi E) {
;     ...
;         const bool has_next = S.next(ui + 1, nxt);
;         const char* nA = has_next ? (const char*)g.A + (size_t)nxt.pm * tstepA : cA; const char* nB = has_next ? (const char*)g.Bt + (size_t)nxt.pn * tstepB : cB;
;     ...
; #pragma unroll
;         for (int a = 0; a < 2; ++a)
; #pragma unroll
;             for (int b = 0; b < 2; ++b)
; #pragma unroll
;                 for (int m = 0; m < 4; ++m)
; #pragma unroll
;                     for (int n = 0; n < 2; ++n) acc[a][b][m][n] = (f32x4){0.f, 0.f, 0.f, 0.f};
.LBB0_1170:
	s_ashr_i32 s17, s16, 31
	s_lshl_b64 s[0:1], s[16:17], 17
	s_add_u32 s18, s20, s0
	s_addc_u32 s19, s21, s1
	s_and_b64 s[0:1], s[42:43], exec
	s_cselect_b32 s17, s19, s25
	s_cselect_b32 s56, s18, s24
	s_ashr_i32 s15, s14, 31
	s_lshl_b64 s[0:1], s[14:15], 17
	v_readlane_b32 s6, v255, 4
	v_readlane_b32 s7, v255, 5
	s_add_u32 s20, s6, s0
	s_addc_u32 s21, s7, s1
	s_and_b64 s[0:1], s[42:43], exec
	v_mov_b32_e32 v2, 0
	s_cselect_b32 s15, s21, s23
	s_cselect_b32 s10, s20, s22
	s_mov_b32 s11, 0
	s_mov_b64 s[26:27], -1
	s_mov_b64 s[28:29], 0
	v_mov_b32_e32 v246, v2
	v_mov_b32_e32 v247, v2
	v_mov_b32_e32 v248, v2
	v_mov_b32_e32 v249, v2
	v_mov_b32_e32 v3, v2
	v_mov_b32_e32 v4, v2
	v_mfma_f32_32x32x16_bf16 v[18:33], v[246:249], v[246:249], 0
	v_mov_b32_e32 v5, v2
	v_mov_b32_e32 v6, v2
	v_mfma_f32_32x32x16_bf16 v[34:49], v[246:249], v[246:249], 0
	v_mov_b32_e32 v7, v2
	v_mov_b32_e32 v8, v2
	v_mfma_f32_32x32x16_bf16 v[50:65], v[246:249], v[246:249], 0
	v_mov_b32_e32 v9, v2
	v_mov_b32_e32 v10, v2
	v_mfma_f32_32x32x16_bf16 v[66:81], v[246:249], v[246:249], 0
	v_mov_b32_e32 v11, v2
	v_mov_b32_e32 v12, v2
	v_mfma_f32_32x32x16_bf16 v[82:97], v[246:249], v[246:249], 0
	v_mov_b32_e32 v13, v2
	v_mov_b32_e32 v14, v2
	v_mfma_f32_32x32x16_bf16 v[98:113], v[246:249], v[246:249], 0
	v_mov_b32_e32 v15, v2
	v_mov_b32_e32 v16, v2
	v_mfma_f32_32x32x16_bf16 v[114:129], v[246:249], v[246:249], 0
	v_mov_b32_e32 v17, v2

; template <class Epi>
; __device__ __forceinline__ void gemm_phase(LAS unsigned char* lds, int wave_s, const Gemm g, const StaticOrder S, const Epi E) {
;     ...
;         const bool has_next = S.next(ui + 1, nxt);
;         const char* nA = has_next ? (const char*)g.A + (size_t)nxt.pm * tstepA : cA; const char* nB = has_next ? (const char*)g.Bt + (size_t)nxt.pn * tstepB : cB;
;     ...
; #pragma unroll
;         for (int a = 0; a < 2; ++a)
; #pragma unroll
;             for (int b = 0; b < 2; ++b)
; #pragma unroll
;                 for (int m = 0; m < 4; ++m)
; #pragma unroll
;                     for (int n = 0; n < 2; ++n) acc[a][b][m][n] = (f32x4){0.f, 0.f, 0.f, 0.f};
.LBB0_1334:
	s_ashr_i32 s49, s48, 31
	s_lshl_b64 s[6:7], s[48:49], 19
	v_readlane_b32 s10, v253, 35
	v_readlane_b32 s11, v253, 36
	s_add_u32 s50, s10, s6
	s_addc_u32 s51, s11, s7
	s_and_b64 s[6:7], s[42:43], exec
	s_cselect_b32 s28, s51, s13
	s_cselect_b32 s29, s50, s12
	s_ashr_i32 s57, s56, 31
	s_lshl_b64 s[6:7], s[56:57], 19
	v_readlane_b32 s10, v253, 31
	v_readlane_b32 s11, v253, 32
	s_add_u32 s52, s10, s6
	s_addc_u32 s53, s11, s7
	s_and_b64 s[6:7], s[42:43], exec
	s_cselect_b32 s10, s53, s15
	s_cselect_b32 s11, s52, s14
	s_add_u32 s12, s12, 0x40080
	s_addc_u32 s13, s13, 0
	s_add_u32 s30, s14, 0x100
	v_mov_b32_e32 v2, 0
	s_addc_u32 s31, s15, 0
	s_mov_b32 s34, -2
	v_mov_b32_e32 v246, v2
	v_mov_b32_e32 v247, v2
	v_mov_b32_e32 v248, v2
	v_mov_b32_e32 v249, v2
	v_mov_b32_e32 v3, v2
	v_mov_b32_e32 v4, v2
	v_mfma_f32_32x32x16_bf16 v[18:33], v[246:249], v[246:249], 0
	v_mov_b32_e32 v5, v2
	v_mov_b32_e32 v6, v2
	v_mfma_f32_32x32x16_bf16 v[34:49], v[246:249], v[246:249], 0
	v_mov_b32_e32 v7, v2
	v_mov_b32_e32 v8, v2
	v_mfma_f32_32x32x16_bf16 v[50:65], v[246:249], v[246:249], 0
	v_mov_b32_e32 v9, v2
	v_mov_b32_e32 v10, v2
	v_mfma_f32_32x32x16_bf16 v[66:81], v[246:249], v[246:249], 0
	v_mov_b32_e32 v11, v2
	v_mov_b32_e32 v12, v2
	v_mfma_f32_32x32x16_bf16 v[82:97], v[246:249], v[246:249], 0
	v_mov_b32_e32 v13, v2
	v_mov_b32_e32 v14, v2
	v_mfma_f32_32x32x16_bf16 v[98:113], v[246:249], v[246:249], 0
	v_mov_b32_e32 v15, v2
	v_mov_b32_e32 v16, v2
	v_mfma_f32_32x32x16_bf16 v[114:129], v[246:249], v[246:249], 0
	v_mov_b32_e32 v17, v2
